# steady attention steps: the post-barrier rescale test branches on VCC directly (s3 flag and its cmp dropped)
# baseline (speedup 1.0000x reference)
.LBB0_974:
	ds_read_b128 v[82:85], v94
	ds_read_b128 v[198:201], v94 offset:512
	ds_read_b128 v[202:205], v94 offset:2048
	ds_read_b128 v[194:197], v94 offset:2560
	s_waitcnt lgkmcnt(4)
	v_mfma_f32_32x32x16_bf16 v[50:65], v[150:153], v[106:109], v[50:65]
	v_exp_f32_e32 v130, v130
	v_exp_f32_e32 v131, v131
	v_exp_f32_e32 v132, v132
	ds_read_b128 v[190:193], v94 offset:4096
	ds_read_b128 v[186:189], v94 offset:4608
	ds_read_b128 v[182:185], v94 offset:6144
	ds_read_b128 v[178:181], v94 offset:6656
	ds_read_b64_tr_b16 v[98:99],v102 offset:3072
	ds_read_b64_tr_b16 v[100:101],v102 offset:3584
	ds_read_b64_tr_b16 v[94:95],v102 offset:2048
	ds_read_b64_tr_b16 v[96:97],v102 offset:2560
	v_mfma_f32_32x32x16_bf16 v[34:49], v[150:153], v[110:113], v[34:49]
	v_exp_f32_e32 v133, v133
	v_exp_f32_e32 v134, v134
	v_exp_f32_e32 v135, v135
	v_mfma_f32_32x32x16_bf16 v[50:65], v[146:149], v[86:89], v[50:65]
	v_exp_f32_e32 v136, v136
	v_exp_f32_e32 v137, v137
	v_exp_f32_e32 v138, v138
	ds_read_b64_tr_b16 v[86:87],v102 offset:0
	ds_read_b64_tr_b16 v[88:89],v102 offset:512
	v_mfma_f32_32x32x16_bf16 v[34:49], v[146:149], v[90:93], v[34:49]
	v_exp_f32_e32 v139, v139
	v_exp_f32_e32 v140, v140
	v_exp_f32_e32 v141, v141
	ds_read_b64_tr_b16 v[90:91],v102 offset:1024
	ds_read_b64_tr_b16 v[92:93],v102 offset:1536
	s_waitcnt lgkmcnt(6)
	v_mfma_f32_32x32x16_bf16 v[18:33], v[146:149], v[98:101], v[18:33]
	v_exp_f32_e32 v142, v142
	v_exp_f32_e32 v143, v143
	v_exp_f32_e32 v144, v144
	ds_read_b64_tr_b16 v[98:99],v102 offset:7168
	ds_read_b64_tr_b16 v[100:101],v102 offset:7680
	s_waitcnt lgkmcnt(6)
	v_mfma_f32_32x32x16_bf16 v[18:33], v[150:153], v[94:97], v[18:33]
	v_exp_f32_e32 v145, v145
	v_exp_f32_e32 v114, v114
	v_exp_f32_e32 v115, v115
	ds_read_b64_tr_b16 v[94:95],v102 offset:6144
	ds_read_b64_tr_b16 v[96:97],v102 offset:6656
	s_waitcnt lgkmcnt(6)
	v_mfma_f32_32x32x16_bf16 v[18:33], v[158:161], v[86:89], v[18:33]
	v_exp_f32_e32 v116, v116
	v_exp_f32_e32 v117, v117
	v_exp_f32_e32 v118, v118
	ds_read_b64_tr_b16 v[86:87],v102 offset:4096
	ds_read_b64_tr_b16 v[88:89],v102 offset:4608
	s_waitcnt lgkmcnt(6)
	v_mfma_f32_32x32x16_bf16 v[18:33], v[154:157], v[90:93], v[18:33]
	v_exp_f32_e32 v119, v119
	v_exp_f32_e32 v120, v120
	v_exp_f32_e32 v121, v121
	ds_read_b64_tr_b16 v[90:91],v102 offset:5120
	ds_read_b64_tr_b16 v[92:93],v102 offset:5632
	s_waitcnt lgkmcnt(6)
	v_mfma_f32_32x32x16_bf16 v[2:17], v[146:149], v[98:101], v[2:17]
	v_exp_f32_e32 v122, v122
	v_exp_f32_e32 v123, v123
	s_waitcnt vmcnt(3) lgkmcnt(0)
	s_barrier
	v_mfma_f32_32x32x16_bf16 v[2:17], v[150:153], v[94:97], v[2:17]
	v_exp_f32_e32 v124, v124
	v_exp_f32_e32 v125, v125
	v_mfma_f32_32x32x16_bf16 v[2:17], v[158:161], v[86:89], v[2:17]
	v_exp_f32_e32 v126, v126
	v_exp_f32_e32 v127, v127
	v_mfma_f32_32x32x16_bf16 v[2:17], v[154:157], v[90:93], v[2:17]
	v_exp_f32_e32 v128, v128
	v_exp_f32_e32 v129, v129
	s_cbranch_vccz .LBB0_976
	s_waitcnt lgkmcnt(0)
	v_add_u32_e32 v229, s94, v243
	ds_read_b128 v[86:89], v229 offset:96
	ds_read_b128 v[90:93], v229 offset:64
	ds_read_b128 v[94:97], v229 offset:32
	ds_read_b128 v[98:101], v229
	s_waitcnt lgkmcnt(3)
	v_pk_mul_f32 v[62:63], v[62:63], v[86:87]
	s_waitcnt lgkmcnt(2)
	v_pk_mul_f32 v[58:59], v[58:59], v[90:91]
	s_waitcnt lgkmcnt(1)
	v_pk_mul_f32 v[54:55], v[54:55], v[94:95]
	v_pk_mul_f32 v[64:65], v[64:65], v[88:89]
	v_pk_mul_f32 v[60:61], v[60:61], v[92:93]
	v_pk_mul_f32 v[56:57], v[56:57], v[96:97]
	s_waitcnt lgkmcnt(0)
	v_pk_mul_f32 v[52:53], v[52:53], v[100:101]
	v_pk_mul_f32 v[50:51], v[50:51], v[98:99]
	v_pk_mul_f32 v[46:47], v[46:47], v[86:87]
	v_pk_mul_f32 v[42:43], v[42:43], v[90:91]
	v_pk_mul_f32 v[38:39], v[38:39], v[94:95]
	v_pk_mul_f32 v[48:49], v[48:49], v[88:89]
	v_pk_mul_f32 v[44:45], v[44:45], v[92:93]
	v_pk_mul_f32 v[40:41], v[40:41], v[96:97]
	v_pk_mul_f32 v[36:37], v[36:37], v[100:101]
	v_pk_mul_f32 v[34:35], v[34:35], v[98:99]
	v_pk_mul_f32 v[30:31], v[30:31], v[86:87]
	v_pk_mul_f32 v[26:27], v[26:27], v[90:91]
	v_pk_mul_f32 v[22:23], v[22:23], v[94:95]
	v_pk_mul_f32 v[32:33], v[32:33], v[88:89]
	v_pk_mul_f32 v[28:29], v[28:29], v[92:93]
	v_pk_mul_f32 v[24:25], v[24:25], v[96:97]
	v_pk_mul_f32 v[20:21], v[20:21], v[100:101]
	v_pk_mul_f32 v[18:19], v[18:19], v[98:99]
	v_pk_mul_f32 v[14:15], v[14:15], v[86:87]
	v_pk_mul_f32 v[10:11], v[10:11], v[90:91]
	v_pk_mul_f32 v[6:7], v[6:7], v[94:95]
	v_pk_mul_f32 v[16:17], v[16:17], v[88:89]
	v_pk_mul_f32 v[12:13], v[12:13], v[92:93]
	v_pk_mul_f32 v[8:9], v[8:9], v[96:97]
	v_pk_mul_f32 v[4:5], v[4:5], v[100:101]
	v_pk_mul_f32 v[2:3], v[2:3], v[98:99]

.LBB0_977:
	v_add_u32_e32 v126, s40, v241
	ds_read_b128 v[206:209], v126
	ds_read_b128 v[202:205], v126 offset:512
	ds_read_b128 v[198:201], v126 offset:2048
	ds_read_b128 v[194:197], v126 offset:2560
	s_waitcnt lgkmcnt(4)
	v_mfma_f32_32x32x16_bf16 v[50:65], v[150:153], v[138:141], v[50:65]
	v_exp_f32_e32 v98, v98
	v_exp_f32_e32 v99, v99
	v_exp_f32_e32 v100, v100
	ds_read_b128 v[190:193], v126 offset:4096
	ds_read_b128 v[186:189], v126 offset:4608
	ds_read_b128 v[182:185], v126 offset:6144
	ds_read_b128 v[178:181], v126 offset:6656
	ds_read_b64_tr_b16 v[126:127],v130 offset:3072
	ds_read_b64_tr_b16 v[128:129],v130 offset:3584
	v_mfma_f32_32x32x16_bf16 v[34:49], v[150:153], v[114:117], v[34:49]
	v_exp_f32_e32 v101, v101
	v_exp_f32_e32 v102, v102
	v_exp_f32_e32 v103, v103
	ds_read_b64_tr_b16 v[114:115],v130 offset:0
	ds_read_b64_tr_b16 v[116:117],v130 offset:512
	v_mfma_f32_32x32x16_bf16 v[50:65], v[146:149], v[118:121], v[50:65]
	v_exp_f32_e32 v104, v104
	v_exp_f32_e32 v105, v105
	v_exp_f32_e32 v106, v106
	ds_read_b64_tr_b16 v[118:119],v130 offset:1024
	ds_read_b64_tr_b16 v[120:121],v130 offset:1536
	v_mfma_f32_32x32x16_bf16 v[34:49], v[146:149], v[122:125], v[34:49]
	v_exp_f32_e32 v107, v107
	v_exp_f32_e32 v108, v108
	v_exp_f32_e32 v109, v109
	ds_read_b64_tr_b16 v[122:123],v130 offset:2048
	ds_read_b64_tr_b16 v[124:125],v130 offset:2560
	s_waitcnt lgkmcnt(6)
	v_mfma_f32_32x32x16_bf16 v[18:33], v[146:149], v[126:129], v[18:33]
	v_exp_f32_e32 v110, v110
	v_exp_f32_e32 v111, v111
	v_exp_f32_e32 v112, v112
	ds_read_b64_tr_b16 v[126:127],v130 offset:7168
	ds_read_b64_tr_b16 v[128:129],v130 offset:7680
	s_waitcnt lgkmcnt(6)
	v_mfma_f32_32x32x16_bf16 v[18:33], v[158:161], v[114:117], v[18:33]
	v_exp_f32_e32 v113, v113
	v_exp_f32_e32 v82, v82
	v_exp_f32_e32 v83, v83
	ds_read_b64_tr_b16 v[114:115],v130 offset:4096
	ds_read_b64_tr_b16 v[116:117],v130 offset:4608
	s_waitcnt lgkmcnt(6)
	v_mfma_f32_32x32x16_bf16 v[18:33], v[154:157], v[118:121], v[18:33]
	v_exp_f32_e32 v84, v84
	v_exp_f32_e32 v85, v85
	v_exp_f32_e32 v86, v86
	ds_read_b64_tr_b16 v[118:119],v130 offset:5120
	ds_read_b64_tr_b16 v[120:121],v130 offset:5632
	s_waitcnt lgkmcnt(6)
	v_mfma_f32_32x32x16_bf16 v[18:33], v[150:153], v[122:125], v[18:33]
	v_exp_f32_e32 v87, v87
	v_exp_f32_e32 v88, v88
	v_exp_f32_e32 v89, v89
	ds_read_b64_tr_b16 v[122:123],v130 offset:6144
	ds_read_b64_tr_b16 v[124:125],v130 offset:6656
	s_waitcnt lgkmcnt(6)
	v_mfma_f32_32x32x16_bf16 v[2:17], v[146:149], v[126:129], v[2:17]
	v_exp_f32_e32 v90, v90
	v_exp_f32_e32 v91, v91
	s_waitcnt vmcnt(3) lgkmcnt(0)
	s_barrier
	v_mfma_f32_32x32x16_bf16 v[2:17], v[158:161], v[114:117], v[2:17]
	v_exp_f32_e32 v92, v92
	v_exp_f32_e32 v93, v93
	v_mfma_f32_32x32x16_bf16 v[2:17], v[154:157], v[118:121], v[2:17]
	v_exp_f32_e32 v94, v94
	v_exp_f32_e32 v95, v95
	v_mfma_f32_32x32x16_bf16 v[2:17], v[150:153], v[122:125], v[2:17]
	v_exp_f32_e32 v96, v96
	v_exp_f32_e32 v97, v97
	s_cbranch_vccz .LBB0_979
	s_waitcnt lgkmcnt(0)
	v_add_u32_e32 v229, s94, v243
	ds_read_b128 v[114:117], v229 offset:96
	ds_read_b128 v[118:121], v229 offset:64
	ds_read_b128 v[122:125], v229 offset:32
	ds_read_b128 v[126:129], v229
	s_waitcnt lgkmcnt(3)
	v_pk_mul_f32 v[62:63], v[62:63], v[114:115]
	s_waitcnt lgkmcnt(2)
	v_pk_mul_f32 v[58:59], v[58:59], v[118:119]
	s_waitcnt lgkmcnt(1)
	v_pk_mul_f32 v[54:55], v[54:55], v[122:123]
	v_pk_mul_f32 v[64:65], v[64:65], v[116:117]
	v_pk_mul_f32 v[60:61], v[60:61], v[120:121]
	v_pk_mul_f32 v[56:57], v[56:57], v[124:125]
	s_waitcnt lgkmcnt(0)
	v_pk_mul_f32 v[52:53], v[52:53], v[128:129]
	v_pk_mul_f32 v[50:51], v[50:51], v[126:127]
	v_pk_mul_f32 v[46:47], v[46:47], v[114:115]
	v_pk_mul_f32 v[42:43], v[42:43], v[118:119]
	v_pk_mul_f32 v[38:39], v[38:39], v[122:123]
	v_pk_mul_f32 v[48:49], v[48:49], v[116:117]
	v_pk_mul_f32 v[44:45], v[44:45], v[120:121]
	v_pk_mul_f32 v[40:41], v[40:41], v[124:125]
	v_pk_mul_f32 v[36:37], v[36:37], v[128:129]
	v_pk_mul_f32 v[34:35], v[34:35], v[126:127]
	v_pk_mul_f32 v[30:31], v[30:31], v[114:115]
	v_pk_mul_f32 v[26:27], v[26:27], v[118:119]
	v_pk_mul_f32 v[22:23], v[22:23], v[122:123]
	v_pk_mul_f32 v[32:33], v[32:33], v[116:117]
	v_pk_mul_f32 v[28:29], v[28:29], v[120:121]
	v_pk_mul_f32 v[24:25], v[24:25], v[124:125]
	v_pk_mul_f32 v[20:21], v[20:21], v[128:129]
	v_pk_mul_f32 v[18:19], v[18:19], v[126:127]
	v_pk_mul_f32 v[14:15], v[14:15], v[114:115]
	v_pk_mul_f32 v[10:11], v[10:11], v[118:119]
	v_pk_mul_f32 v[6:7], v[6:7], v[122:123]
	v_pk_mul_f32 v[16:17], v[16:17], v[116:117]
	v_pk_mul_f32 v[12:13], v[12:13], v[120:121]
	v_pk_mul_f32 v[8:9], v[8:9], v[124:125]
	v_pk_mul_f32 v[4:5], v[4:5], v[128:129]
	v_pk_mul_f32 v[2:3], v[2:3], v[126:127]

.LBB0_1080:
	ds_read_b128 v[82:85], v94
	ds_read_b128 v[198:201], v94 offset:512
	ds_read_b128 v[202:205], v94 offset:2048
	ds_read_b128 v[194:197], v94 offset:2560
	s_waitcnt lgkmcnt(4)
	v_mfma_f32_32x32x16_bf16 v[50:65], v[158:161], v[106:109], v[50:65]
	v_exp_f32_e32 v130, v130
	v_exp_f32_e32 v131, v131
	v_exp_f32_e32 v132, v132
	ds_read_b128 v[190:193], v94 offset:4096
	ds_read_b128 v[186:189], v94 offset:4608
	ds_read_b128 v[182:185], v94 offset:6144
	ds_read_b128 v[178:181], v94 offset:6656
	ds_read_b64_tr_b16 v[98:99],v102 offset:3072
	ds_read_b64_tr_b16 v[100:101],v102 offset:3584
	ds_read_b64_tr_b16 v[94:95],v102 offset:2048
	ds_read_b64_tr_b16 v[96:97],v102 offset:2560
	v_mfma_f32_32x32x16_bf16 v[34:49], v[158:161], v[110:113], v[34:49]
	v_exp_f32_e32 v133, v133
	v_exp_f32_e32 v134, v134
	v_exp_f32_e32 v135, v135
	v_mfma_f32_32x32x16_bf16 v[50:65], v[154:157], v[86:89], v[50:65]
	v_exp_f32_e32 v136, v136
	v_exp_f32_e32 v137, v137
	v_exp_f32_e32 v138, v138
	ds_read_b64_tr_b16 v[86:87],v102 offset:0
	ds_read_b64_tr_b16 v[88:89],v102 offset:512
	v_mfma_f32_32x32x16_bf16 v[34:49], v[154:157], v[90:93], v[34:49]
	v_exp_f32_e32 v139, v139
	v_exp_f32_e32 v140, v140
	v_exp_f32_e32 v141, v141
	ds_read_b64_tr_b16 v[90:91],v102 offset:1024
	ds_read_b64_tr_b16 v[92:93],v102 offset:1536
	s_waitcnt lgkmcnt(6)
	v_mfma_f32_32x32x16_bf16 v[18:33], v[154:157], v[98:101], v[18:33]
	v_exp_f32_e32 v142, v142
	v_exp_f32_e32 v143, v143
	v_exp_f32_e32 v144, v144
	ds_read_b64_tr_b16 v[98:99],v102 offset:7168
	ds_read_b64_tr_b16 v[100:101],v102 offset:7680
	s_waitcnt lgkmcnt(6)
	v_mfma_f32_32x32x16_bf16 v[18:33], v[158:161], v[94:97], v[18:33]
	v_exp_f32_e32 v145, v145
	v_exp_f32_e32 v114, v114
	v_exp_f32_e32 v115, v115
	ds_read_b64_tr_b16 v[94:95],v102 offset:6144
	ds_read_b64_tr_b16 v[96:97],v102 offset:6656
	s_waitcnt lgkmcnt(6)
	v_mfma_f32_32x32x16_bf16 v[18:33], v[166:169], v[86:89], v[18:33]
	v_exp_f32_e32 v116, v116
	v_exp_f32_e32 v117, v117
	v_exp_f32_e32 v118, v118
	ds_read_b64_tr_b16 v[86:87],v102 offset:4096
	ds_read_b64_tr_b16 v[88:89],v102 offset:4608
	s_waitcnt lgkmcnt(6)
	v_mfma_f32_32x32x16_bf16 v[18:33], v[162:165], v[90:93], v[18:33]
	v_exp_f32_e32 v119, v119
	v_exp_f32_e32 v120, v120
	v_exp_f32_e32 v121, v121
	ds_read_b64_tr_b16 v[90:91],v102 offset:5120
	ds_read_b64_tr_b16 v[92:93],v102 offset:5632
	s_waitcnt lgkmcnt(6)
	v_mfma_f32_32x32x16_bf16 v[2:17], v[154:157], v[98:101], v[2:17]
	v_exp_f32_e32 v122, v122
	v_exp_f32_e32 v123, v123
	s_waitcnt vmcnt(3) lgkmcnt(0)
	s_barrier
	v_mfma_f32_32x32x16_bf16 v[2:17], v[158:161], v[94:97], v[2:17]
	v_exp_f32_e32 v124, v124
	v_exp_f32_e32 v125, v125
	v_mfma_f32_32x32x16_bf16 v[2:17], v[166:169], v[86:89], v[2:17]
	v_exp_f32_e32 v126, v126
	v_exp_f32_e32 v127, v127
	v_mfma_f32_32x32x16_bf16 v[2:17], v[162:165], v[90:93], v[2:17]
	v_exp_f32_e32 v128, v128
	v_exp_f32_e32 v129, v129
	s_cbranch_vccz .LBB0_1082
	s_waitcnt lgkmcnt(0)
	v_add_u32_e32 v229, s39, v243
	ds_read_b128 v[86:89], v229 offset:96
	ds_read_b128 v[90:93], v229 offset:64
	ds_read_b128 v[94:97], v229 offset:32
	ds_read_b128 v[98:101], v229
	s_waitcnt lgkmcnt(3)
	v_pk_mul_f32 v[62:63], v[62:63], v[86:87]
	s_waitcnt lgkmcnt(2)
	v_pk_mul_f32 v[58:59], v[58:59], v[90:91]
	s_waitcnt lgkmcnt(1)
	v_pk_mul_f32 v[54:55], v[54:55], v[94:95]
	v_pk_mul_f32 v[64:65], v[64:65], v[88:89]
	v_pk_mul_f32 v[60:61], v[60:61], v[92:93]
	v_pk_mul_f32 v[56:57], v[56:57], v[96:97]
	s_waitcnt lgkmcnt(0)
	v_pk_mul_f32 v[52:53], v[52:53], v[100:101]
	v_pk_mul_f32 v[50:51], v[50:51], v[98:99]
	v_pk_mul_f32 v[46:47], v[46:47], v[86:87]
	v_pk_mul_f32 v[42:43], v[42:43], v[90:91]
	v_pk_mul_f32 v[38:39], v[38:39], v[94:95]
	v_pk_mul_f32 v[48:49], v[48:49], v[88:89]
	v_pk_mul_f32 v[44:45], v[44:45], v[92:93]
	v_pk_mul_f32 v[40:41], v[40:41], v[96:97]
	v_pk_mul_f32 v[36:37], v[36:37], v[100:101]
	v_pk_mul_f32 v[34:35], v[34:35], v[98:99]
	v_pk_mul_f32 v[30:31], v[30:31], v[86:87]
	v_pk_mul_f32 v[26:27], v[26:27], v[90:91]
	v_pk_mul_f32 v[22:23], v[22:23], v[94:95]
	v_pk_mul_f32 v[32:33], v[32:33], v[88:89]
	v_pk_mul_f32 v[28:29], v[28:29], v[92:93]
	v_pk_mul_f32 v[24:25], v[24:25], v[96:97]
	v_pk_mul_f32 v[20:21], v[20:21], v[100:101]
	v_pk_mul_f32 v[18:19], v[18:19], v[98:99]
	v_pk_mul_f32 v[14:15], v[14:15], v[86:87]
	v_pk_mul_f32 v[10:11], v[10:11], v[90:91]
	v_pk_mul_f32 v[6:7], v[6:7], v[94:95]
	v_pk_mul_f32 v[16:17], v[16:17], v[88:89]
	v_pk_mul_f32 v[12:13], v[12:13], v[92:93]
	v_pk_mul_f32 v[8:9], v[8:9], v[96:97]
	v_pk_mul_f32 v[4:5], v[4:5], v[100:101]
	v_pk_mul_f32 v[2:3], v[2:3], v[98:99]

.LBB0_1083:
	v_add_u32_e32 v126, s40, v241
	ds_read_b128 v[206:209], v126
	ds_read_b128 v[198:201], v126 offset:512
	ds_read_b128 v[202:205], v126 offset:2048
	ds_read_b128 v[194:197], v126 offset:2560
	s_waitcnt lgkmcnt(4)
	v_mfma_f32_32x32x16_bf16 v[50:65], v[158:161], v[138:141], v[50:65]
	v_exp_f32_e32 v98, v98
	v_exp_f32_e32 v99, v99
	v_exp_f32_e32 v100, v100
	ds_read_b128 v[190:193], v126 offset:4096
	ds_read_b128 v[186:189], v126 offset:4608
	ds_read_b128 v[182:185], v126 offset:6144
	ds_read_b128 v[178:181], v126 offset:6656
	ds_read_b64_tr_b16 v[126:127],v130 offset:3072
	ds_read_b64_tr_b16 v[128:129],v130 offset:3584
	v_mfma_f32_32x32x16_bf16 v[34:49], v[158:161], v[114:117], v[34:49]
	v_exp_f32_e32 v101, v101
	v_exp_f32_e32 v102, v102
	v_exp_f32_e32 v103, v103
	ds_read_b64_tr_b16 v[114:115],v130 offset:0
	ds_read_b64_tr_b16 v[116:117],v130 offset:512
	v_mfma_f32_32x32x16_bf16 v[50:65], v[154:157], v[118:121], v[50:65]
	v_exp_f32_e32 v104, v104
	v_exp_f32_e32 v105, v105
	v_exp_f32_e32 v106, v106
	ds_read_b64_tr_b16 v[118:119],v130 offset:1024
	ds_read_b64_tr_b16 v[120:121],v130 offset:1536
	v_mfma_f32_32x32x16_bf16 v[34:49], v[154:157], v[122:125], v[34:49]
	v_exp_f32_e32 v107, v107
	v_exp_f32_e32 v108, v108
	v_exp_f32_e32 v109, v109
	ds_read_b64_tr_b16 v[122:123],v130 offset:2048
	ds_read_b64_tr_b16 v[124:125],v130 offset:2560
	s_waitcnt lgkmcnt(6)
	v_mfma_f32_32x32x16_bf16 v[18:33], v[154:157], v[126:129], v[18:33]
	v_exp_f32_e32 v110, v110
	v_exp_f32_e32 v111, v111
	v_exp_f32_e32 v112, v112
	ds_read_b64_tr_b16 v[126:127],v130 offset:7168
	ds_read_b64_tr_b16 v[128:129],v130 offset:7680
	s_waitcnt lgkmcnt(6)
	v_mfma_f32_32x32x16_bf16 v[18:33], v[166:169], v[114:117], v[18:33]
	v_exp_f32_e32 v113, v113
	v_exp_f32_e32 v82, v82
	v_exp_f32_e32 v83, v83
	ds_read_b64_tr_b16 v[114:115],v130 offset:4096
	ds_read_b64_tr_b16 v[116:117],v130 offset:4608
	s_waitcnt lgkmcnt(6)
	v_mfma_f32_32x32x16_bf16 v[18:33], v[162:165], v[118:121], v[18:33]
	v_exp_f32_e32 v84, v84
	v_exp_f32_e32 v85, v85
	v_exp_f32_e32 v86, v86
	ds_read_b64_tr_b16 v[118:119],v130 offset:5120
	ds_read_b64_tr_b16 v[120:121],v130 offset:5632
	s_waitcnt lgkmcnt(6)
	v_mfma_f32_32x32x16_bf16 v[18:33], v[158:161], v[122:125], v[18:33]
	v_exp_f32_e32 v87, v87
	v_exp_f32_e32 v88, v88
	v_exp_f32_e32 v89, v89
	ds_read_b64_tr_b16 v[122:123],v130 offset:6144
	ds_read_b64_tr_b16 v[124:125],v130 offset:6656
	s_waitcnt lgkmcnt(6)
	v_mfma_f32_32x32x16_bf16 v[2:17], v[154:157], v[126:129], v[2:17]
	v_exp_f32_e32 v90, v90
	v_exp_f32_e32 v91, v91
	s_waitcnt vmcnt(3) lgkmcnt(0)
	s_barrier
	v_mfma_f32_32x32x16_bf16 v[2:17], v[166:169], v[114:117], v[2:17]
	v_exp_f32_e32 v92, v92
	v_exp_f32_e32 v93, v93
	v_mfma_f32_32x32x16_bf16 v[2:17], v[162:165], v[118:121], v[2:17]
	v_exp_f32_e32 v94, v94
	v_exp_f32_e32 v95, v95
	v_mfma_f32_32x32x16_bf16 v[2:17], v[158:161], v[122:125], v[2:17]
	v_exp_f32_e32 v96, v96
	v_exp_f32_e32 v97, v97
	s_cbranch_vccz .LBB0_1085
	s_waitcnt lgkmcnt(0)
	v_add_u32_e32 v229, s39, v243
	ds_read_b128 v[114:117], v229 offset:96
	ds_read_b128 v[118:121], v229 offset:64
	ds_read_b128 v[122:125], v229 offset:32
	ds_read_b128 v[126:129], v229
	s_waitcnt lgkmcnt(3)
	v_pk_mul_f32 v[62:63], v[62:63], v[114:115]
	s_waitcnt lgkmcnt(2)
	v_pk_mul_f32 v[58:59], v[58:59], v[118:119]
	s_waitcnt lgkmcnt(1)
	v_pk_mul_f32 v[54:55], v[54:55], v[122:123]
	v_pk_mul_f32 v[64:65], v[64:65], v[116:117]
	v_pk_mul_f32 v[60:61], v[60:61], v[120:121]
	v_pk_mul_f32 v[56:57], v[56:57], v[124:125]
	s_waitcnt lgkmcnt(0)
	v_pk_mul_f32 v[52:53], v[52:53], v[128:129]
	v_pk_mul_f32 v[50:51], v[50:51], v[126:127]
	v_pk_mul_f32 v[46:47], v[46:47], v[114:115]
	v_pk_mul_f32 v[42:43], v[42:43], v[118:119]
	v_pk_mul_f32 v[38:39], v[38:39], v[122:123]
	v_pk_mul_f32 v[48:49], v[48:49], v[116:117]
	v_pk_mul_f32 v[44:45], v[44:45], v[120:121]
	v_pk_mul_f32 v[40:41], v[40:41], v[124:125]
	v_pk_mul_f32 v[36:37], v[36:37], v[128:129]
	v_pk_mul_f32 v[34:35], v[34:35], v[126:127]
	v_pk_mul_f32 v[30:31], v[30:31], v[114:115]
	v_pk_mul_f32 v[26:27], v[26:27], v[118:119]
	v_pk_mul_f32 v[22:23], v[22:23], v[122:123]
	v_pk_mul_f32 v[32:33], v[32:33], v[116:117]
	v_pk_mul_f32 v[28:29], v[28:29], v[120:121]
	v_pk_mul_f32 v[24:25], v[24:25], v[124:125]
	v_pk_mul_f32 v[20:21], v[20:21], v[128:129]
	v_pk_mul_f32 v[18:19], v[18:19], v[126:127]
	v_pk_mul_f32 v[14:15], v[14:15], v[114:115]
	v_pk_mul_f32 v[10:11], v[10:11], v[118:119]
	v_pk_mul_f32 v[6:7], v[6:7], v[122:123]
	v_pk_mul_f32 v[16:17], v[16:17], v[116:117]
	v_pk_mul_f32 v[12:13], v[12:13], v[120:121]
	v_pk_mul_f32 v[8:9], v[8:9], v[124:125]
	v_pk_mul_f32 v[4:5], v[4:5], v[128:129]
	v_pk_mul_f32 v[2:3], v[2:3], v[126:127]
